# P + FFN2 gate-half weight conversion moved from P1's tail (112 CUs, contending with GEMM round 6) to after P11's short GEMM (all CUs)
# baseline (speedup 1.0000x reference)
; #define LAS __attribute__((address_space(3)))
; #define INP(i) ((const float*)ldptr(ptab, (i)))
; __global__ void __launch_bounds__(512, 2) fwd_mega(Args args) {
;     ...
;               if (G == 256 && bx >= first) { __syncthreads(); LAS float* scr = (LAS float*)(lds + wave * 17664);
;                   for (int it = (bx - first) * 8 + wave; it < 88 * 32; it += (256 - first) * 8) p0_tr(ph == 1 ? INP(5) : INP(25), DFF, DM, ph == 1 ? Wd1 : Wd2, 128, 0, scr, it, lane);
;                   if (ph == 1) for (int it = (bx - first) * 8 + wave; it < 32 * 88; it += (256 - first) * 8) p0_tr(INP(23), DM, DFF, Wgu2, 256, 0, scr, it, lane, INP(22)); }
;               else if (G != 256) { __syncthreads(); LAS float* scr = (LAS float*)(lds + wave * 17664);
;                   for (int it = gw; it < 88 * 32; it += NGW) p0_tr(ph == 1 ? INP(5) : INP(25), DFF, DM, ph == 1 ? Wd1 : Wd2, 128, 0, scr, it, lane);
;                   if (ph == 1) for (int it = gw; it < 32 * 88; it += NGW) p0_tr(INP(23), DM, DFF, Wgu2, 256, 0, scr, it, lane, INP(22)); } }
;         } else if (ph == 2 || ph == 8 || ph == 11 || ph == 13) {
;             const bf16* A = (ph == 2 || ph == 13) ? ACT : (ph == 8 ? MIX : OX);
;             const bf16* Bt = ph == 2 ? Wd1 : (ph == 8 ? Wout : (ph == 11 ? Wo : Wd2));
;             const int K = (ph == 2 || ph == 13) ? DFF : (ph == 8 ? DM : 512);
;             pg8::Gemm g{A, Bt, TOK, DM, K}; pg8::StaticOrder S; S.init(TOK, DM, G, bx);
;             pg8::EpiResid E{(const float*)nullptr  , Hb, ph == 13 ? xres : (float*)nullptr, ph == 13 ? nullptr : SSQ, (ph == 2 || ph == 13) ? 0.5f : 1.0f};
;             pg8::gemm_phase<pg8::EpiResid, pg8::StaticOrder, true, true>(lds, g, S, E);
.LBB0_321:
	s_cmp_lg_u32 s50, 11
	s_cbranch_scc1 .LBB0_582
	s_cmpk_lg_i32 s52, 0x100
	s_cbranch_scc1 .LBB0_582
	v_readlane_b32 s12, v255, 51
	s_lshl_b32 s0, s2, 3
	s_mov_b32 s14, 0
	s_mul_i32 s15, s12, 0x4500
	s_add_i32 s0, s0, s12
	s_branch .Lconv2_entry

; #define LAS __attribute__((address_space(3)))
; #define LDS_WAIT() asm volatile("s_waitcnt lgkmcnt(0)" ::: "memory")
; #define INP(i) ((const float*)ldptr(ptab, (i)))
; __device__ __forceinline__ void p0_tr(const float* __restrict__ W, int K, int N, bf16* WT, int rstride, int roff, LAS float* scr, int item, int lane, const float* gk = nullptr) {
;     const int nblk = (N + 63) / 64, kb = item / nblk, nb = item % nblk, k0 = 64 * kb, n0 = 64 * nb;
;     const int kq = lane >> 4, n4 = (lane & 15) * 4;
;     const bool ok = (n0 + n4) < N;
;     f32x4 v[16];
; #pragma unroll
;     for (int i = 0; i < 16; ++i) v[i] = ok ? __builtin_nontemporal_load((const f32x4*)(W + (size_t)(k0 + 4 * i + kq) * N + n0 + n4)) : (f32x4){0.f, 0.f, 0.f, 0.f};
; #pragma unroll
;     for (int i = 0; i < 16; ++i)
; #pragma unroll
;         for (int e = 0; e < 4; ++e) scr[(4 * i + kq) * 69 + n4 + e] = v[i][e];
;     LDS_WAIT(); asm volatile("" ::: "memory");
;     const int c = lane & 7;
;     f32x4 ga = {1.f, 1.f, 1.f, 1.f}, gb = {1.f, 1.f, 1.f, 1.f};
;     if (gk) { ga = *(const f32x4*)(gk + k0 + 8 * c); gb = *(const f32x4*)(gk + k0 + 8 * c + 4); }
; #pragma unroll
;     for (int j = 0; j < 8; ++j) { const int n = (lane >> 3) + 8 * j, gn = n0 + n; const LAS float* sp = scr + (8 * c) * 69 + n;
; __global__ void __launch_bounds__(512, 2) fwd_mega(Args args) {
;     ...
;               if (G == 256 && bx >= first) { __syncthreads(); LAS float* scr = (LAS float*)(lds + wave * 17664);
;                   for (int it = (bx - first) * 8 + wave; it < 88 * 32; it += (256 - first) * 8) p0_tr(ph == 1 ? INP(5) : INP(25), DFF, DM, ph == 1 ? Wd1 : Wd2, 128, 0, scr, it, lane);
;                   if (ph == 1) for (int it = (bx - first) * 8 + wave; it < 32 * 88; it += (256 - first) * 8) p0_tr(INP(23), DM, DFF, Wgu2, 256, 0, scr, it, lane, INP(22)); }
.LBB0_418:
	s_mov_b64 s[12:13], 0
	s_andn2_b64 vcc, exec, s[12:13]
	s_cbranch_vccnz .LBB0_471
.Lconv2_entry:
	v_lshlrev_b32_e32 v0, 2, v154
	v_lshrrev_b32_e32 v65, 4, v154
	v_and_b32_e32 v64, 60, v0
	v_and_b32_e32 v3, 7, v238
	v_lshrrev_b32_e32 v70, 3, v154
	v_readlane_b32 s12, v255, 58
	v_lshl_add_u32 v1, v64, 2, s15
	v_mul_u32_u24_e32 v2, 0x114, v65
	v_lshlrev_b32_e32 v0, 3, v3
	v_mul_u32_u24_e32 v4, 0x8a0, v3
	v_lshlrev_b32_e32 v5, 2, v70
	v_lshlrev_b32_e32 v152, 4, v3
	v_readlane_b32 s13, v255, 59
	v_add3_u32 v71, s15, v4, v5
	v_or_b32_e32 v72, 8, v70
	v_or_b32_e32 v73, 16, v70
	v_or_b32_e32 v74, 24, v70
	v_or_b32_e32 v75, 32, v70
	v_or_b32_e32 v76, 40, v70
	v_or_b32_e32 v77, 48, v70
	v_or_b32_e32 v78, 56, v70
	s_lshl_b32 s14, s14, 3
	v_lshl_add_u64 v[66:67], s[12:13], 0, v[152:153]
	v_add_u32_e32 v79, v1, v2
	v_lshlrev_b32_e32 v80, 2, v0
	s_branch .LBB0_421
